# MLA loop: second-half probabilities packed early into separate registers so all second-half exps sit under PV MFMAs
# speedup vs baseline: 1.0112x; 1.0058x over previous
; #define MFMA(a, b, c) __builtin_amdgcn_mfma_f32_32x32x16_bf16((a), (b), (c), 0, 0, 0)
; DI unsigned pk2(float a, float b) { f2_t v = {a, b}; bf2_t r = __builtin_convertvector(v, bf2_t); return __builtin_bit_cast(unsigned, r); }
; DI float xhalf_sum(float x) { const auto rr = __builtin_amdgcn_permlane32_swap(__float_as_uint(x), __float_as_uint(x), false, false); return __uint_as_float(rr[0]) + __uint_as_float(rr[1]); }
; template <int DQK, int DV, bool BAND> ...
;     ...
;       const float m_ref = (m_run == -INFINITY) ? 0.f : m_run;
;       float rs0 = 0.f, rs1 = 0.f;
; #pragma unroll
;       for (int r = 0; r < 16; ++r) { const float e0 = __builtin_amdgcn_exp2f(p0[r] - m_ref), e1 = __builtin_amdgcn_exp2f(p1[r] - m_ref); p0[r] = e0; p1[r] = e1; rs0 += e0; rs1 += e1; }
;       l_run += xhalf_sum(rs0 + rs1);
;       __builtin_amdgcn_s_setprio(1);
; #pragma unroll
;       for (int s = 0; s < 2; ++s) {
;         const u32x4 pu0 = {pk2(p0[8 * s], p0[8 * s + 1]), pk2(p0[8 * s + 2], p0[8 * s + 3]), pk2(p0[8 * s + 4], p0[8 * s + 5]), pk2(p0[8 * s + 6], p0[8 * s + 7])};
;         const u32x4 pu1 = {pk2(p1[8 * s], p1[8 * s + 1]), pk2(p1[8 * s + 2], p1[8 * s + 3]), pk2(p1[8 * s + 4], p1[8 * s + 5]), pk2(p1[8 * s + 6], p1[8 * s + 7])};
; #pragma unroll
;         for (int cb = 0; cb < NCB; ++cb) {
;           const u32x2 lo0 = *(const u32x2*)&Vs[(cb * 32 + r32) * VLD + 16 * s + 4 * hi];
;           const u32x2 hi0 = *(const u32x2*)&Vs[(cb * 32 + r32) * VLD + 16 * s + 4 * hi + 8];
;           const u32x4 v0 = {lo0[0], lo0[1], hi0[0], hi0[1]};
;           o[cb] = MFMA(__builtin_bit_cast(bf16x8, pu0), __builtin_bit_cast(bf16x8, v0), o[cb]);
;         }
; #pragma unroll
;         for (int cb = 0; cb < NCB; ++cb) {
;           const u32x2 lo1 = *(const u32x2*)&Vs[(cb * 32 + r32) * VLD + 32 + 16 * s + 4 * hi];
;           const u32x2 hi1 = *(const u32x2*)&Vs[(cb * 32 + r32) * VLD + 32 + 16 * s + 4 * hi + 8];
;           const u32x4 v1 = {lo1[0], lo1[1], hi1[0], hi1[1]};
;           o[cb] = MFMA(__builtin_bit_cast(bf16x8, pu1), __builtin_bit_cast(bf16x8, v1), o[cb]);
;         }
;       }
;       __builtin_amdgcn_s_setprio(0);
.LBB1_325:
	v_exp_f32_e32 v34, v34
	v_exp_f32_e32 v35, v35
	v_exp_f32_e32 v36, v36
	v_exp_f32_e32 v37, v37
	v_exp_f32_e32 v38, v38
	v_exp_f32_e32 v39, v39
	v_exp_f32_e32 v40, v40
	v_exp_f32_e32 v41, v41
	v_exp_f32_e32 v42, v42
	v_exp_f32_e32 v43, v43
	v_exp_f32_e32 v44, v44
	v_exp_f32_e32 v45, v45
	v_exp_f32_e32 v46, v46
	v_exp_f32_e32 v47, v47
	v_exp_f32_e32 v48, v48
	v_exp_f32_e32 v49, v49
	s_nop 0
	v_pk_add_f32 v[168:169], v[34:35], v[36:37]
	v_pk_add_f32 v[170:171], v[38:39], v[40:41]
	v_pk_add_f32 v[168:169], v[42:43], v[168:169]
	v_pk_add_f32 v[170:171], v[44:45], v[170:171]
	v_pk_add_f32 v[168:169], v[46:47], v[168:169]
	v_pk_add_f32 v[170:171], v[48:49], v[170:171]
	v_cvt_pk_bf16_f32 v34, v34, v35
	v_cvt_pk_bf16_f32 v35, v36, v37
	v_cvt_pk_bf16_f32 v36, v38, v39
	v_cvt_pk_bf16_f32 v37, v40, v41
	v_cvt_pk_bf16_f32 v38, v42, v43
	v_cvt_pk_bf16_f32 v39, v44, v45
	v_cvt_pk_bf16_f32 v40, v46, v47
	v_cvt_pk_bf16_f32 v41, v48, v49
	v_exp_f32_e32 v50, v50
	v_exp_f32_e32 v51, v51
	v_exp_f32_e32 v52, v52
	s_waitcnt lgkmcnt(0)
	v_mfma_f32_32x32x16_bf16 v[2:17], v[34:37], v[208:211], v[2:17]
	v_exp_f32_e32 v53, v53
	v_exp_f32_e32 v54, v54
	v_exp_f32_e32 v55, v55
	v_mfma_f32_32x32x16_bf16 v[18:33], v[34:37], v[212:215], v[18:33]
	v_exp_f32_e32 v56, v56
	v_exp_f32_e32 v57, v57
	v_exp_f32_e32 v58, v58
	v_mfma_f32_32x32x16_bf16 v[2:17], v[38:41], v[224:227], v[2:17]
	v_exp_f32_e32 v59, v59
	v_exp_f32_e32 v60, v60
	v_exp_f32_e32 v61, v61
	v_mfma_f32_32x32x16_bf16 v[18:33], v[38:41], v[228:231], v[18:33]
	v_cvt_pk_bf16_f32 v240, v50, v51
	v_cvt_pk_bf16_f32 v241, v52, v53
	v_cvt_pk_bf16_f32 v242, v54, v55
	v_cvt_pk_bf16_f32 v243, v56, v57
	v_exp_f32_e32 v62, v62
	v_mfma_f32_32x32x16_bf16 v[2:17], v[240:243], v[216:219], v[2:17]
	v_exp_f32_e32 v63, v63
	v_exp_f32_e32 v64, v64
	v_exp_f32_e32 v65, v65
	v_mfma_f32_32x32x16_bf16 v[18:33], v[240:243], v[220:223], v[18:33]
	v_pk_add_f32 v[168:169], v[50:51], v[168:169]
	v_pk_add_f32 v[170:171], v[52:53], v[170:171]
	v_pk_add_f32 v[168:169], v[54:55], v[168:169]
	v_pk_add_f32 v[170:171], v[56:57], v[170:171]
	v_pk_add_f32 v[168:169], v[58:59], v[168:169]
	v_pk_add_f32 v[170:171], v[60:61], v[170:171]
	v_pk_add_f32 v[168:169], v[62:63], v[168:169]
	v_pk_add_f32 v[170:171], v[64:65], v[170:171]
	v_pk_add_f32 v[168:169], v[168:169], v[170:171]
	v_cvt_pk_bf16_f32 v54, v58, v59
	v_cvt_pk_bf16_f32 v55, v60, v61
	v_cvt_pk_bf16_f32 v56, v62, v63
	v_cvt_pk_bf16_f32 v57, v64, v65
	v_add_f32_e32 v168, v168, v169
	v_mov_b32_e32 v169, v168
	v_mfma_f32_32x32x16_bf16 v[2:17], v[54:57], v[232:235], v[2:17]
	s_nop 0
	v_permlane32_swap_b32_e32 v168, v169
	v_add_f32_e32 v168, v168, v169
	v_add_f32_e32 v126, v126, v168
	v_mfma_f32_32x32x16_bf16 v[18:33], v[54:57], v[236:239], v[18:33]
	s_add_u32 s12, s12, s8
	s_addc_u32 s13, s13, s9
	s_add_u32 s14, s14, s10
	s_addc_u32 s15, s15, s11
	s_cmp_eq_u32 s75, s21
	s_cbranch_scc1 .LBB1_327
	v_mov_b32_e32 v133, v0
	s_branch .LBB1_318
